# attention queue: next unit index fetched at the start of the current unit's output epilogue
# speedup vs baseline: 1.0053x; 1.0001x over previous
.LBB0_760:
	s_mov_b32 s100, 0
	s_add_i32 s6, s18, s95
	s_ashr_i32 s7, s6, 31
	s_abs_i32 s6, s6
	s_mul_hi_u32 s19, s6, s94
	s_mul_i32 s19, s19, s3
	s_sub_i32 s6, s6, s19
	s_sub_i32 s19, s6, s3
	s_cmp_ge_u32 s6, s3
	s_cselect_b32 s6, s19, s6
	s_sub_i32 s19, s6, s3
	s_cmp_ge_u32 s6, s3
	s_cselect_b32 s6, s19, s6
	s_xor_b32 s6, s6, s7
	s_sub_i32 s19, s6, s7
	s_lshl_b32 s6, s19, 6
	s_ashr_i32 s7, s6, 31
	s_lshl_b64 s[6:7], s[6:7], 2
	s_add_u32 s76, s92, s6
	s_addc_u32 s77, s93, s7
	s_lshl_b32 s19, s19, 3
	s_branch .LBB0_763
.LBB0_761:
	s_or_b64 exec, exec, s[6:7]
	s_and_saveexec_b64 s[98:99], s[0:1]
	s_cbranch_execz .Lapf_skip
	v_mov_b32_e32 v253, 1
	global_atomic_add v253, v99, v253, s[76:77] sc0
.Lapf_skip:
	s_mov_b64 exec, s[98:99]
	s_mov_b32 s100, 1
	s_waitcnt lgkmcnt(0)
	ds_read_b128 v[32:35], v65 offset:49280
	ds_read_b128 v[36:39], v65 offset:49312
	s_lshl_b64 s[6:7], s[78:79], 1
	s_add_u32 s6, s68, s6
	s_addc_u32 s7, s69, s7
	s_waitcnt lgkmcnt(1)
	v_rcp_f32_e32 v40, v32
	v_rcp_f32_e32 v41, v33
	s_lshl_b32 s21, s21, 12
	s_add_i32 s21, s21, 0
	v_lshlrev_b32_e32 v48, 1, v206
	v_mul_f32_e32 v0, v0, v40
	v_add3_u32 v48, s21, v214, v48
	v_cvt_pk_bf16_f32 v0, v0, s0
	v_rcp_f32_e32 v42, v34
	v_rcp_f32_e32 v43, v35
	s_waitcnt lgkmcnt(0)
	v_rcp_f32_e32 v44, v36
	ds_read_b128 v[32:35], v65 offset:49344
	v_rcp_f32_e32 v45, v37
	v_rcp_f32_e32 v46, v38
	v_rcp_f32_e32 v47, v39
	ds_read_b128 v[36:39], v65 offset:49376
	ds_write_b16 v48, v0 offset:51264
	v_mul_f32_e32 v0, v17, v41
	v_cvt_pk_bf16_f32 v0, v0, s0
	ds_write_b16 v48, v0 offset:51328
	v_mul_f32_e32 v0, v1, v41
	v_cvt_pk_bf16_f32 v0, v0, s0
	ds_write_b16 v48, v0 offset:51392
	v_mul_f32_e32 v0, v18, v42
	v_cvt_pk_bf16_f32 v0, v0, s0
	ds_write_b16 v48, v0 offset:51456
	v_mul_f32_e32 v0, v2, v42
	v_cvt_pk_bf16_f32 v0, v0, s0
	ds_write_b16 v48, v0 offset:51520
	v_mul_f32_e32 v0, v19, v43
	v_cvt_pk_bf16_f32 v0, v0, s0
	ds_write_b16 v48, v0 offset:51584
	v_mul_f32_e32 v0, v3, v43
	v_cvt_pk_bf16_f32 v0, v0, s0
	ds_write_b16 v48, v0 offset:51648
	v_mul_f32_e32 v0, v20, v44
	v_cvt_pk_bf16_f32 v0, v0, s0
	ds_write_b16 v48, v0 offset:52224
	v_mul_f32_e32 v0, v4, v44
	v_cvt_pk_bf16_f32 v0, v0, s0
	ds_write_b16 v48, v0 offset:52288
	v_mul_f32_e32 v0, v21, v45
	v_cvt_pk_bf16_f32 v0, v0, s0
	ds_write_b16 v48, v0 offset:52352
	v_mul_f32_e32 v0, v5, v45
	v_cvt_pk_bf16_f32 v0, v0, s0
	ds_write_b16 v48, v0 offset:52416
	v_mul_f32_e32 v0, v22, v46
	v_cvt_pk_bf16_f32 v0, v0, s0
	ds_write_b16 v48, v0 offset:52480
	v_mul_f32_e32 v0, v6, v46
	v_cvt_pk_bf16_f32 v0, v0, s0
	s_waitcnt lgkmcnt(13)
	v_rcp_f32_e32 v32, v32
	ds_write_b16 v48, v0 offset:52544
	v_mul_f32_e32 v0, v23, v47
	v_cvt_pk_bf16_f32 v0, v0, s0
	ds_write_b16 v48, v0 offset:52608
	v_mul_f32_e32 v0, v7, v47
	v_cvt_pk_bf16_f32 v0, v0, s0
	v_rcp_f32_e32 v33, v33
	ds_write_b16 v48, v0 offset:52672
	v_mul_f32_e32 v0, v24, v32
	v_cvt_pk_bf16_f32 v0, v0, s0
	ds_write_b16 v48, v0 offset:53248
	v_mul_f32_e32 v0, v8, v32
	v_cvt_pk_bf16_f32 v0, v0, s0
	v_rcp_f32_e32 v34, v34
	ds_write_b16 v48, v0 offset:53312
	v_mul_f32_e32 v0, v25, v33
	v_cvt_pk_bf16_f32 v0, v0, s0
	ds_write_b16 v48, v0 offset:53376
	v_mul_f32_e32 v0, v9, v33
	v_cvt_pk_bf16_f32 v0, v0, s0
	v_rcp_f32_e32 v35, v35
	ds_write_b16 v48, v0 offset:53440
	v_mul_f32_e32 v0, v26, v34
	v_cvt_pk_bf16_f32 v0, v0, s0
	ds_write_b16 v48, v0 offset:53504
	v_mul_f32_e32 v0, v10, v34
	v_cvt_pk_bf16_f32 v0, v0, s0
	s_waitcnt lgkmcnt(14)
	v_rcp_f32_e32 v36, v36
	ds_write_b16 v48, v0 offset:53568
	v_mul_f32_e32 v0, v27, v35
	v_cvt_pk_bf16_f32 v0, v0, s0
	ds_write_b16 v48, v0 offset:53632
	v_mul_f32_e32 v0, v11, v35
	v_cvt_pk_bf16_f32 v0, v0, s0
	v_rcp_f32_e32 v37, v37
	ds_write_b16 v48, v0 offset:53696
	v_mul_f32_e32 v0, v28, v36
	v_cvt_pk_bf16_f32 v0, v0, s0
	ds_write_b16 v48, v0 offset:54272
	v_mul_f32_e32 v0, v12, v36
	v_cvt_pk_bf16_f32 v0, v0, s0
	v_rcp_f32_e32 v38, v38
	ds_write_b16 v48, v0 offset:54336
	v_mul_f32_e32 v0, v29, v37
	v_cvt_pk_bf16_f32 v0, v0, s0
	ds_write_b16 v48, v0 offset:54400
	v_mul_f32_e32 v0, v13, v37
	v_cvt_pk_bf16_f32 v0, v0, s0
	v_rcp_f32_e32 v39, v39
	ds_write_b16 v48, v0 offset:54464
	v_mul_f32_e32 v0, v30, v38
	v_cvt_pk_bf16_f32 v0, v0, s0
	ds_write_b16 v48, v0 offset:54528
	v_mul_f32_e32 v0, v14, v38
	v_cvt_pk_bf16_f32 v0, v0, s0
	ds_write_b16 v48, v0 offset:54592
	v_mul_f32_e32 v0, v31, v39
	v_cvt_pk_bf16_f32 v0, v0, s0
	v_mul_f32_e32 v16, v16, v40
	ds_write_b16 v48, v0 offset:54656
	v_mul_f32_e32 v0, v15, v39
	v_cvt_pk_bf16_f32 v16, v16, s0
	v_cvt_pk_bf16_f32 v0, v0, s0
	ds_write_b16 v48, v16 offset:51200
	ds_write_b16 v48, v0 offset:54720
	v_add_u32_e32 v12, s21, v192
	s_waitcnt lgkmcnt(0)
	v_add_u32_e32 v0, v12, v215
	ds_read_b128 v[0:3], v0 offset:51200
	v_add_u32_e32 v4, v12, v216
	s_add_u32 s6, s6, s20
	ds_read_b128 v[4:7], v4 offset:51200
	s_addc_u32 s7, s7, 0
	v_mov_b32_e32 v193, v99
	v_lshl_add_u64 v[8:9], s[6:7], 0, v[192:193]
	v_mov_b32_e32 v195, v99
	v_lshl_add_u64 v[10:11], v[8:9], 0, v[194:195]
	v_mov_b32_e32 v197, v99
	s_waitcnt lgkmcnt(1)
	global_store_dwordx4 v[10:11], v[0:3], off
	v_mov_b32_e32 v199, v99
	v_lshl_add_u64 v[10:11], v[8:9], 0, v[198:199]
	v_lshl_add_u64 v[0:1], v[8:9], 0, v[196:197]
	s_waitcnt lgkmcnt(0)
	global_store_dwordx4 v[0:1], v[4:7], off
	v_add_u32_e32 v0, v12, v217
	ds_read_b128 v[0:3], v0 offset:51200
	v_add_u32_e32 v4, v12, v218
	ds_read_b128 v[4:7], v4 offset:51200
	v_mov_b32_e32 v201, v99
	s_mov_b64 s[6:7], 0
	s_waitcnt lgkmcnt(1)
	global_store_dwordx4 v[10:11], v[0:3], off
	s_nop 1
	v_lshl_add_u64 v[0:1], v[8:9], 0, v[200:201]
	s_waitcnt lgkmcnt(0)
	global_store_dwordx4 v[0:1], v[4:7], off
	s_waitcnt lgkmcnt(0)
	s_barrier

.LBB0_763:
	s_and_saveexec_b64 s[6:7], s[0:1]
	s_cbranch_execz .LBB0_767
	s_mov_b64 s[56:57], exec
	v_mbcnt_lo_u32_b32 v0, s56, 0
	v_mbcnt_hi_u32_b32 v0, s57, v0
	v_cmp_eq_u32_e32 vcc, 0, v0
	s_and_saveexec_b64 s[54:55], vcc
	s_cbranch_execz .LBB0_766
	s_cmp_eq_u32 s100, 0
	s_cbranch_scc0 .Lapf_have
	s_bcnt1_i32_b64 s20, s[56:57]
	v_mov_b32_e32 v1, s20
	global_atomic_add v1, v99, v1, s[76:77] sc0
	s_branch .Lapf_join
.Lapf_have:
	s_waitcnt vmcnt(0)
	v_mov_b32_e32 v1, v253
.Lapf_join:
.LBB0_766:
	s_or_b64 exec, exec, s[54:55]
	s_waitcnt vmcnt(0)
	v_readfirstlane_b32 s20, v1
	v_mov_b32_e32 v1, s16
	s_nop 0
	v_add_u32_e32 v0, s20, v0
	ds_write_b32 v1, v0
